# steady-state attention steps: exps spread 2 per MFMA gap over 16 gaps, next-tile C-operand init moved into the new PV MFMA gaps as scalar v_fma (was v_pk_fma after the MFMAs); counted vmcnt for the ex
# speedup vs baseline: 1.0074x; 1.0074x over previous
; #define WAIT_BAR(N) asm volatile("s_waitcnt vmcnt(" #N ") lgkmcnt(0)\n\ts_barrier":::"memory")
;   #define DMA_K(t,slot) glds16(ksrc+(long)(t)*KVBLK*PIN,(unsigned)__builtin_amdgcn_readfirstlane(kdst+(slot)))
;   #define DMA_V(t,slot) glds16(vsrc+(long)(t)*KVBLK*PIN,(unsigned)__builtin_amdgcn_readfirstlane(vdst+(slot)))
;   #define CINIT(C0,C1,btl) do{ const float b_=(btl); _Pragma("unroll") for(int r=0;r<16;++r){ C0[r]=__builtin_fmaf(s2,(float)((r&3)+8*(r>>2)),b_); C1[r]=__builtin_fmaf(s2,(float)((r&3)+8*(r>>2)+32),b_);} }while(0)
;   #define CMASK(P0,P1,t) do{ if(WIN||(t)>=NT-4)gmask(P0,P1,64*(t),qrel,hi,WIN);}while(0)
;   #define START(P0,P1) do{ resc=false; \
;     if(!NOMAX){ const float rm=rowmax(P0,P1); const float dl=__builtin_fmaxf(rm,0.f);     \
;       mhat=fadd_s(mhat,dl); \
;       _Pragma("unroll") for(int r=0;r<16;++r){P0[r]=fsub_s(P0[r],dl);P1[r]=fsub_s(P1[r],dl);} } \
;     _Pragma("unroll") for(int r=0;r<16;++r)P0[r]=__builtin_amdgcn_exp2f(P0[r]); }while(0)
;   #define ROT() do{sl_prev=sl_cur;sl_cur=sl_next;sl_next=(sl_next==(NSLOT-1)*SLOTB)?0:sl_next+SLOTB;}while(0)
;   #define CMASK(P0,P1,t) do{}while(0)
;   #define CMASK(P0,P1,t) do{ if(WIN||(t)>=NT-4)gmask(P0,P1,64*(t),qrel,hi,WIN);}while(0)
; template<int THRL> __device__ __forceinline__ void attn_unit(long rowbase,int qb,int t0,bool WIN,bool NOMAX,const bf16*Qc,const bf16*__restrict__ Kc,const bf16*__restrict__ Vc,bf16*Oc,float s2,float sink2,char*shm,
;     bf16x8 (&qr)[4],bool pref,const bf16*qkvb,int vn,int in_){
;     ...
;   CINIT(pA0,pA1,-qb2); qkt(pA0,pA1,Kbase,qr,r32,hi);asm volatile("s_nop 15\n\ts_nop 7":"+v"(pA0),"+v"(pA1));CMASK(pA0,pA1,0);
;   START(pA0,pA1);
;   _Pragma("unroll") for(int r=0;r<16;++r)pA1[r]=__builtin_amdgcn_exp2f(pA1[r]);
;   WAIT_BAR(0);
;   DMA_K(3,0);DMA_V(1,SLOTB);
;   ROT();
;   kload8(kf,kp0+sl_cur);
;   CINIT(pB0,pB1,__builtin_fmaf(s2,64.f,-qb2)-mhat); asm volatile("":"+v"(pB0)); asm volatile("":"+v"(pB1));
;   WAIT_BAR(2);
;   s16x4 vlo[8],vhi[8]; u32x4 pw0,pw1,pw2,pw3;
.LBB0_332:
	s_or_b64 exec, exec, s[42:43]
	s_and_b32 s42, s44, 0x3fffffc0
	s_lshl_b32 s42, s42, 2
	s_add_i32 s44, s42, 0
	s_waitcnt vmcnt(0) lgkmcnt(0)
	s_barrier
	s_mov_b64 s[64:65], 0xd8000
	v_exp_f32_e32 v114, v18
	v_exp_f32_e32 v115, v19
	v_lshl_add_u64 v[18:19], v[194:195], 0, s[64:65]
	s_mov_b32 s42, m0
	s_mov_b32 m0, s50
	s_nop 0
	global_load_lds_dwordx4 v[18:19], off
	s_mov_b32 m0, s42
	s_cmp_lg_u32 0, -1
	s_cselect_b32 s42, 0, 0
	s_add_i32 s42, s42, s82
	v_lshl_add_u64 v[192:193], v[82:83], 0, s[6:7]
	s_add_i32 s42, s42, 0x8000
	s_mov_b32 s43, m0
	s_mov_b32 m0, s42
	s_nop 0
	global_load_lds_dwordx4 v[192:193], off
	s_add_i32 m0, s42, 0xe780
	s_nop 0
	global_load_lds_dwordx4 v[192:193], off offset:128
	s_mov_b32 m0, s43
	ds_read_b128 v[174:177], v231 offset:8192
	ds_read_b128 v[170:173], v231 offset:8704
	ds_read_b128 v[166:169], v231 offset:10240
	ds_read_b128 v[162:165], v231 offset:10752
	ds_read_b128 v[158:161], v231 offset:12288
	ds_read_b128 v[154:157], v231 offset:12800
	ds_read_b128 v[150:153], v231 offset:14336
	ds_read_b128 v[146:149], v231 offset:14848
	v_lshlrev_b32_e32 v51, 1, v50
	v_lshrrev_b32_e32 v50, 2, v50
	v_and_b32_e32 v229, 32, v51
	v_and_or_b32 v50, v50, 3, v230
	v_fmamk_f32 v18, v184, 0x42800000, v186
	v_lshlrev_b32_e32 v226, 6, v50
	v_add_u32_e32 v50, 0, v229
	v_sub_f32_e32 v18, v18, v225
	v_mov_b32_e32 v185, v184
	v_add3_u32 v232, v50, v219, v226
	v_exp_f32_e32 v116, v20
	v_exp_f32_e32 v117, v21
	v_exp_f32_e32 v118, v22
	v_exp_f32_e32 v119, v23
	v_exp_f32_e32 v120, v24
	v_exp_f32_e32 v121, v25
	v_exp_f32_e32 v122, v26
	v_exp_f32_e32 v123, v27
	v_exp_f32_e32 v124, v28
	v_exp_f32_e32 v125, v29
	v_exp_f32_e32 v126, v30
	v_exp_f32_e32 v127, v31
	v_exp_f32_e32 v128, v32
	v_exp_f32_e32 v129, v33
	v_exp_f32_e32 v98, v34
	v_exp_f32_e32 v99, v35
	v_exp_f32_e32 v100, v36
	v_exp_f32_e32 v101, v37
	v_exp_f32_e32 v102, v38
	v_exp_f32_e32 v103, v39
	v_exp_f32_e32 v104, v40
	v_exp_f32_e32 v105, v41
	v_exp_f32_e32 v106, v42
	v_exp_f32_e32 v107, v43
	v_exp_f32_e32 v108, v44
	v_exp_f32_e32 v109, v45
	v_exp_f32_e32 v110, v46
	v_exp_f32_e32 v111, v47
	v_exp_f32_e32 v112, v48
	v_exp_f32_e32 v113, v49
	v_fma_f32 v66, 0, v184, v18
	v_add_f32_e32 v67, v184, v18
	v_pk_fma_f32 v[68:69], v[190:191], s[8:9], v[18:19] op_sel_hi:[1,1,0]
	v_pk_fma_f32 v[70:71], v[190:191], s[10:11], v[18:19] op_sel_hi:[1,1,0]
	v_pk_fma_f32 v[72:73], v[190:191], s[12:13], v[18:19] op_sel_hi:[1,1,0]
	v_pk_fma_f32 v[74:75], v[190:191], s[14:15], v[18:19] op_sel_hi:[1,1,0]
	v_pk_fma_f32 v[76:77], v[190:191], s[16:17], v[18:19] op_sel_hi:[1,1,0]
	v_pk_fma_f32 v[78:79], v[190:191], s[18:19], v[18:19] op_sel_hi:[1,1,0]
	v_pk_fma_f32 v[80:81], v[190:191], s[20:21], v[18:19] op_sel_hi:[1,1,0]
	v_pk_fma_f32 v[64:65], v[184:185], s[22:23], v[18:19] op_sel_hi:[1,1,0]
	v_pk_fma_f32 v[62:63], v[184:185], s[24:25], v[18:19] op_sel_hi:[1,1,0]
	v_pk_fma_f32 v[60:61], v[184:185], s[26:27], v[18:19] op_sel_hi:[1,1,0]
	v_pk_fma_f32 v[58:59], v[184:185], s[28:29], v[18:19] op_sel_hi:[1,1,0]
	v_pk_fma_f32 v[56:57], v[184:185], s[30:31], v[18:19] op_sel_hi:[1,1,0]
	v_pk_fma_f32 v[54:55], v[184:185], s[34:35], v[18:19] op_sel_hi:[1,1,0]
	v_pk_fma_f32 v[52:53], v[184:185], s[36:37], v[18:19] op_sel_hi:[1,1,0]
	v_pk_fma_f32 v[50:51], v[188:189], s[92:93], v[18:19] op_sel_hi:[1,1,0]
	s_mov_b32 s67, 1
	s_waitcnt vmcnt(3) lgkmcnt(0)
	s_barrier
	v_mov_b32_e32 v236, 0
	v_mov_b32_e32 v237, 0
	v_mov_b32_e32 v238, 0
	v_mov_b32_e32 v239, 0
	v_mov_b32_e32 v240, 0
	v_mov_b32_e32 v241, 0
	v_mov_b32_e32 v242, 0
	v_mov_b32_e32 v243, 0
	v_mov_b32_e32 v244, 0
	v_mov_b32_e32 v245, 0
	v_mov_b32_e32 v246, 0
	v_mov_b32_e32 v247, 0
	v_mov_b32_e32 v248, 0
	v_mov_b32_e32 v249, 0
	v_mov_b32_e32 v250, 0
	v_mov_b32_e32 v251, 0
	v_mov_b32_e32 v200, 0
	v_mov_b32_e32 v201, 0
	v_mov_b32_e32 v202, 0
	v_mov_b32_e32 v203, 0
	v_mov_b32_e32 v204, 0
	v_mov_b32_e32 v205, 0
	v_mov_b32_e32 v206, 0
	v_mov_b32_e32 v207, 0
	v_mov_b32_e32 v208, 0
	v_mov_b32_e32 v209, 0
	v_mov_b32_e32 v210, 0
	v_mov_b32_e32 v211, 0
	v_mov_b32_e32 v212, 0
	v_mov_b32_e32 v213, 0
	v_mov_b32_e32 v214, 0
	v_mov_b32_e32 v215, 0
	s_mov_b32 s66, 0
	s_cmp_lt_i32 s4, 7
	v_cmp_gt_u32_e64 s[42:43], 32, v183
	v_lshl_add_u32 v228, v180, 2, s44
	v_lshl_add_u32 v227, v230, 2, s44
	s_cbranch_scc1 .LBB0_355
	v_mov_b32_e32 v32, v1
	v_mov_b32_e32 v33, v1
	s_mov_b64 s[44:45], 0x168000
	v_mov_b32_e32 v18, v1
	v_mov_b32_e32 v19, v1
	v_mov_b32_e32 v20, v1
	v_mov_b32_e32 v21, v1
	v_mov_b32_e32 v22, v1
	v_mov_b32_e32 v23, v1
	v_mov_b32_e32 v24, v1
	v_mov_b32_e32 v25, v1
	v_mov_b32_e32 v26, v1
	v_mov_b32_e32 v27, v1
	v_mov_b32_e32 v28, v1
	v_mov_b32_e32 v29, v1
	v_mov_b32_e32 v30, v1
	v_mov_b32_e32 v31, v1
	v_mov_b64_e32 v[48:49], v[32:33]
	s_add_i32 s48, s4, -5
	v_lshl_add_u64 v[196:197], v[82:83], 0, s[64:65]
	v_lshl_add_u64 v[198:199], v[194:195], 0, s[44:45]
	s_mov_b32 s44, 0
	s_movk_i32 s66, 0x4000
	s_movk_i32 s51, 0x2000
	v_mov_b32_e32 v82, 0
	s_movk_i32 s49, 0xc0
	v_mov_b64_e32 v[46:47], v[30:31]
	v_mov_b64_e32 v[44:45], v[28:29]
	v_mov_b64_e32 v[42:43], v[26:27]
	v_mov_b64_e32 v[40:41], v[24:25]
	v_mov_b64_e32 v[38:39], v[22:23]
	v_mov_b64_e32 v[36:37], v[20:21]
	v_mov_b64_e32 v[34:35], v[18:19]

.LBB0_337:
	s_or_b64 exec, exec, s[64:65]
	s_waitcnt lgkmcnt(14)
	v_mfma_f32_32x32x16_bf16 v[18:33], v[142:145], v[84:87], v[18:33]
	v_exp_f32_e32 v66, v66
	v_exp_f32_e32 v67, v67
	s_waitcnt lgkmcnt(12)
	v_mfma_f32_32x32x16_bf16 v[34:49], v[142:145], v[88:91], v[34:49]
	v_exp_f32_e32 v68, v68
	v_exp_f32_e32 v69, v69
	v_add_u32_e32 v82, s66, v231
	ds_read_b128 v[162:165], v82
	ds_read_b128 v[158:161], v82 offset:512
	s_waitcnt lgkmcnt(12)
	v_mfma_f32_32x32x16_bf16 v[18:33], v[138:141], v[92:95], v[18:33]
	v_exp_f32_e32 v70, v70
	v_exp_f32_e32 v71, v71
	ds_read_b128 v[154:157], v82 offset:2048
	ds_read_b128 v[146:149], v82 offset:2560
	s_waitcnt lgkmcnt(12)
	v_mfma_f32_32x32x16_bf16 v[34:49], v[138:141], v[114:117], v[34:49]
	v_exp_f32_e32 v72, v72
	v_exp_f32_e32 v73, v73
	ds_read_b128 v[94:97], v82 offset:4096
	ds_read_b128 v[90:93], v82 offset:4608
	s_waitcnt lgkmcnt(12)
	v_mfma_f32_32x32x16_bf16 v[18:33], v[134:137], v[118:121], v[18:33]
	v_exp_f32_e32 v74, v74
	v_exp_f32_e32 v75, v75
	ds_read_b128 v[86:89], v82 offset:6144
	ds_read_b128 v[82:85], v82 offset:6656
	s_waitcnt lgkmcnt(12)
	v_mfma_f32_32x32x16_bf16 v[34:49], v[134:137], v[98:101], v[34:49]
	v_exp_f32_e32 v76, v76
	v_exp_f32_e32 v77, v77
	s_waitcnt lgkmcnt(10)
	v_mfma_f32_32x32x16_bf16 v[18:33], v[130:133], v[102:105], v[18:33]
	v_exp_f32_e32 v78, v78
	v_exp_f32_e32 v79, v79
	s_waitcnt lgkmcnt(8)
	v_mfma_f32_32x32x16_bf16 v[34:49], v[130:133], v[106:109], v[34:49]
	v_exp_f32_e32 v80, v80
	v_exp_f32_e32 v81, v81
	ds_read_b64_tr_b16 v[98:99], v255 offset:24576
	ds_read_b64_tr_b16 v[100:101], v255 offset:25088
	ds_read_b64_tr_b16 v[102:103], v255 offset:28672
	ds_read_b64_tr_b16 v[104:105], v255 offset:29184
	ds_read_b64_tr_b16 v[106:107], v255 offset:25600
	ds_read_b64_tr_b16 v[108:109], v255 offset:26112
	ds_read_b64_tr_b16 v[110:111], v255 offset:29696
	ds_read_b64_tr_b16 v[112:113], v255 offset:30208
	ds_read_b64_tr_b16 v[114:115], v255 offset:26624
	ds_read_b64_tr_b16 v[116:117], v255 offset:27136
	ds_read_b64_tr_b16 v[118:119], v255 offset:30720
	ds_read_b64_tr_b16 v[120:121], v255 offset:31232
	ds_read_b64_tr_b16 v[122:123], v255 offset:27648
	ds_read_b64_tr_b16 v[124:125], v255 offset:28160
	ds_read_b64_tr_b16 v[126:127], v255 offset:31744
	ds_read_b64_tr_b16 v[128:129], v255 offset:32256
	s_sub_i32 s64, s49, 64
	v_exp_f32_e32 v50, v50
	v_exp_f32_e32 v51, v51
	v_exp_f32_e32 v52, v52
	v_exp_f32_e32 v53, v53
	v_exp_f32_e32 v54, v54
	v_exp_f32_e32 v55, v55
	v_exp_f32_e32 v56, v56
	v_exp_f32_e32 v57, v57
	s_waitcnt lgkmcnt(14)
	v_mfma_f32_32x32x16_bf16 v[236:251], v[142:145], v[98:101], v[236:251]
	v_cvt_f32_u32_e32 v98, s64
	v_mov_b32_e32 v185, v184
	v_fma_f32 v98, v184, v98, v186
	v_sub_f32_e32 v98, v98, v225
	v_exp_f32_e32 v58, v58
	s_waitcnt lgkmcnt(12)
	v_mfma_f32_32x32x16_bf16 v[200:215], v[142:145], v[102:105], v[200:215]
	v_fma_f32 v105, v185, s31, v98
	v_fma_f32 v104, v184, s30, v98
	v_fma_f32 v103, v185, s35, v98
	v_fma_f32 v102, v184, s34, v98
	v_exp_f32_e32 v59, v59
	s_waitcnt lgkmcnt(10)
	v_mfma_f32_32x32x16_bf16 v[236:251], v[138:141], v[106:109], v[236:251]
	v_fma_f32 v109, v185, s27, v98
	v_fma_f32 v108, v184, s26, v98
	v_fma_f32 v107, v185, s29, v98
	v_fma_f32 v106, v184, s28, v98
	v_exp_f32_e32 v60, v60
	s_waitcnt lgkmcnt(8)
	v_mfma_f32_32x32x16_bf16 v[200:215], v[138:141], v[110:113], v[200:215]
	v_fma_f32 v113, v185, s23, v98
	v_fma_f32 v112, v184, s22, v98
	v_fma_f32 v111, v185, s25, v98
	v_fma_f32 v110, v184, s24, v98
	v_exp_f32_e32 v61, v61
	s_waitcnt lgkmcnt(6)
	v_mfma_f32_32x32x16_bf16 v[236:251], v[134:137], v[114:117], v[236:251]
	v_fma_f32 v114, 0, v184, v98
	v_add_f32_e32 v115, v184, v98
	v_fma_f32 v117, v191, s9, v98
	v_fma_f32 v116, v190, s8, v98
	v_exp_f32_e32 v62, v62
	s_waitcnt lgkmcnt(4)
	v_mfma_f32_32x32x16_bf16 v[200:215], v[134:137], v[118:121], v[200:215]
	v_fma_f32 v119, v191, s11, v98
	v_fma_f32 v118, v190, s10, v98
	v_fma_f32 v121, v191, s13, v98
	v_fma_f32 v120, v190, s12, v98
	v_exp_f32_e32 v63, v63
	s_waitcnt lgkmcnt(2)
	v_mfma_f32_32x32x16_bf16 v[236:251], v[130:133], v[122:125], v[236:251]
	v_fma_f32 v123, v191, s15, v98
	v_fma_f32 v122, v190, s14, v98
	v_fma_f32 v125, v191, s17, v98
	v_fma_f32 v124, v190, s16, v98
	v_exp_f32_e32 v64, v64
	s_waitcnt lgkmcnt(0)
	v_mfma_f32_32x32x16_bf16 v[200:215], v[130:133], v[126:129], v[200:215]
	v_fma_f32 v127, v191, s19, v98
	v_fma_f32 v126, v190, s18, v98
	v_fma_f32 v129, v191, s21, v98
	v_fma_f32 v128, v190, s20, v98
	v_exp_f32_e32 v65, v65
	v_fma_f32 v101, v185, s37, v98
	v_fma_f32 v100, v184, s36, v98
	v_fma_f32 v99, v189, s93, v98
	v_fma_f32 v98, v188, s92, v98
	s_nop 0
	s_waitcnt vmcnt(3) lgkmcnt(0)
	s_barrier
	s_and_saveexec_b64 s[64:65], s[44:45]
	s_cbranch_execz .LBB0_339
	s_waitcnt lgkmcnt(0)
	ds_read_b128 v[150:153], v227 offset:49248
	ds_read_b128 v[168:171], v227 offset:49216
	ds_read_b128 v[172:175], v227 offset:49184
	s_waitcnt lgkmcnt(2)
	v_pk_mul_f32 v[32:33], v[32:33], v[152:153]
	v_pk_mul_f32 v[30:31], v[30:31], v[150:151]
	v_pk_mul_f32 v[48:49], v[48:49], v[152:153]
	v_pk_mul_f32 v[46:47], v[46:47], v[150:151]
	v_pk_mul_f32 v[250:251], v[250:251], v[152:153]
	v_pk_mul_f32 v[248:249], v[248:249], v[150:151]
	v_pk_mul_f32 v[214:215], v[214:215], v[152:153]
	v_pk_mul_f32 v[212:213], v[212:213], v[150:151]
	ds_read_b128 v[150:153], v227 offset:49152
	s_waitcnt lgkmcnt(2)
	v_pk_mul_f32 v[28:29], v[28:29], v[170:171]
	v_pk_mul_f32 v[26:27], v[26:27], v[168:169]
	v_pk_mul_f32 v[44:45], v[44:45], v[170:171]
	v_pk_mul_f32 v[42:43], v[42:43], v[168:169]
	v_pk_mul_f32 v[246:247], v[246:247], v[170:171]
	v_pk_mul_f32 v[244:245], v[244:245], v[168:169]
	v_pk_mul_f32 v[210:211], v[210:211], v[170:171]
	v_pk_mul_f32 v[208:209], v[208:209], v[168:169]
	s_waitcnt lgkmcnt(1)
	v_pk_mul_f32 v[24:25], v[24:25], v[174:175]
	v_pk_mul_f32 v[22:23], v[22:23], v[172:173]
	v_pk_mul_f32 v[40:41], v[40:41], v[174:175]
	v_pk_mul_f32 v[38:39], v[38:39], v[172:173]
	v_pk_mul_f32 v[242:243], v[242:243], v[174:175]
	v_pk_mul_f32 v[240:241], v[240:241], v[172:173]
	v_pk_mul_f32 v[206:207], v[206:207], v[174:175]
	v_pk_mul_f32 v[204:205], v[204:205], v[172:173]
	s_waitcnt lgkmcnt(0)
	v_pk_mul_f32 v[20:21], v[20:21], v[152:153]
	v_pk_mul_f32 v[18:19], v[18:19], v[150:151]
	v_pk_mul_f32 v[36:37], v[36:37], v[152:153]
	v_pk_mul_f32 v[34:35], v[34:35], v[150:151]
	v_pk_mul_f32 v[238:239], v[238:239], v[152:153]
	v_pk_mul_f32 v[236:237], v[236:237], v[150:151]
	v_pk_mul_f32 v[202:203], v[202:203], v[152:153]
	v_pk_mul_f32 v[200:201], v[200:201], v[150:151]

.LBB0_342:
	s_or_b64 exec, exec, s[64:65]
	s_waitcnt lgkmcnt(14)
	v_mfma_f32_32x32x16_bf16 v[18:33], v[142:145], v[150:153], v[18:33]
	v_exp_f32_e32 v114, v114
	v_exp_f32_e32 v115, v115
	s_waitcnt lgkmcnt(12)
	v_mfma_f32_32x32x16_bf16 v[34:49], v[142:145], v[66:69], v[34:49]
	v_exp_f32_e32 v116, v116
	v_exp_f32_e32 v117, v117
	v_add_u32_e32 v62, s86, v231
	ds_read_b128 v[174:177], v62
	ds_read_b128 v[170:173], v62 offset:512
	s_waitcnt lgkmcnt(12)
	v_mfma_f32_32x32x16_bf16 v[18:33], v[138:141], v[70:73], v[18:33]
	v_exp_f32_e32 v118, v118
	v_exp_f32_e32 v119, v119
	ds_read_b128 v[166:169], v62 offset:2048
	ds_read_b128 v[162:165], v62 offset:2560
	s_waitcnt lgkmcnt(12)
	v_mfma_f32_32x32x16_bf16 v[34:49], v[138:141], v[74:77], v[34:49]
	v_exp_f32_e32 v120, v120
	v_exp_f32_e32 v121, v121
	ds_read_b128 v[158:161], v62 offset:4096
	ds_read_b128 v[154:157], v62 offset:4608
	s_waitcnt lgkmcnt(12)
	v_mfma_f32_32x32x16_bf16 v[18:33], v[134:137], v[78:81], v[18:33]
	v_exp_f32_e32 v122, v122
	v_exp_f32_e32 v123, v123
	ds_read_b128 v[150:153], v62 offset:6144
	ds_read_b128 v[146:149], v62 offset:6656
	s_waitcnt lgkmcnt(12)
	v_mfma_f32_32x32x16_bf16 v[34:49], v[134:137], v[50:53], v[34:49]
	v_exp_f32_e32 v124, v124
	v_exp_f32_e32 v125, v125
	s_waitcnt lgkmcnt(10)
	v_mfma_f32_32x32x16_bf16 v[18:33], v[130:133], v[54:57], v[18:33]
	v_exp_f32_e32 v126, v126
	v_exp_f32_e32 v127, v127
	s_waitcnt lgkmcnt(8)
	v_mfma_f32_32x32x16_bf16 v[34:49], v[130:133], v[58:61], v[34:49]
	v_exp_f32_e32 v128, v128
	v_exp_f32_e32 v129, v129
	ds_read_b64_tr_b16 v[50:51], v255 offset:24576
	ds_read_b64_tr_b16 v[52:53], v255 offset:25088
	ds_read_b64_tr_b16 v[54:55], v255 offset:28672
	ds_read_b64_tr_b16 v[56:57], v255 offset:29184
	ds_read_b64_tr_b16 v[58:59], v255 offset:25600
	ds_read_b64_tr_b16 v[60:61], v255 offset:26112
	ds_read_b64_tr_b16 v[62:63], v255 offset:29696
	ds_read_b64_tr_b16 v[64:65], v255 offset:30208
	ds_read_b64_tr_b16 v[66:67], v255 offset:26624
	ds_read_b64_tr_b16 v[68:69], v255 offset:27136
	ds_read_b64_tr_b16 v[70:71], v255 offset:30720
	ds_read_b64_tr_b16 v[72:73], v255 offset:31232
	ds_read_b64_tr_b16 v[74:75], v255 offset:27648
	ds_read_b64_tr_b16 v[76:77], v255 offset:28160
	ds_read_b64_tr_b16 v[78:79], v255 offset:31744
	ds_read_b64_tr_b16 v[80:81], v255 offset:32256
	v_exp_f32_e32 v98, v98
	v_exp_f32_e32 v99, v99
	v_exp_f32_e32 v100, v100
	v_exp_f32_e32 v101, v101
	v_exp_f32_e32 v102, v102
	v_exp_f32_e32 v103, v103
	v_exp_f32_e32 v104, v104
	v_exp_f32_e32 v105, v105
	s_waitcnt lgkmcnt(14)
	v_mfma_f32_32x32x16_bf16 v[236:251], v[142:145], v[50:53], v[236:251]
	v_cvt_f32_u32_e32 v50, s49
	v_mov_b32_e32 v185, v184
	v_fma_f32 v50, v184, v50, v186
	v_sub_f32_e32 v50, v50, v225
	v_exp_f32_e32 v106, v106
	s_waitcnt lgkmcnt(12)
	v_mfma_f32_32x32x16_bf16 v[200:215], v[142:145], v[54:57], v[200:215]
	v_fma_f32 v57, v185, s31, v50
	v_fma_f32 v56, v184, s30, v50
	v_fma_f32 v55, v185, s35, v50
	v_fma_f32 v54, v184, s34, v50
	v_exp_f32_e32 v107, v107
	s_waitcnt lgkmcnt(10)
	v_mfma_f32_32x32x16_bf16 v[236:251], v[138:141], v[58:61], v[236:251]
	v_fma_f32 v61, v185, s27, v50
	v_fma_f32 v60, v184, s26, v50
	v_fma_f32 v59, v185, s29, v50
	v_fma_f32 v58, v184, s28, v50
	v_exp_f32_e32 v108, v108
	s_waitcnt lgkmcnt(8)
	v_mfma_f32_32x32x16_bf16 v[200:215], v[138:141], v[62:65], v[200:215]
	v_fma_f32 v65, v185, s23, v50
	v_fma_f32 v64, v184, s22, v50
	v_fma_f32 v63, v185, s25, v50
	v_fma_f32 v62, v184, s24, v50
	v_exp_f32_e32 v109, v109
	s_waitcnt lgkmcnt(6)
	v_mfma_f32_32x32x16_bf16 v[236:251], v[134:137], v[66:69], v[236:251]
	v_fma_f32 v66, 0, v184, v50
	v_add_f32_e32 v67, v184, v50
	v_fma_f32 v69, v191, s9, v50
	v_fma_f32 v68, v190, s8, v50
	v_exp_f32_e32 v110, v110
	s_waitcnt lgkmcnt(4)
	v_mfma_f32_32x32x16_bf16 v[200:215], v[134:137], v[70:73], v[200:215]
	v_fma_f32 v71, v191, s11, v50
	v_fma_f32 v70, v190, s10, v50
	v_fma_f32 v73, v191, s13, v50
	v_fma_f32 v72, v190, s12, v50
	v_exp_f32_e32 v111, v111
	s_waitcnt lgkmcnt(2)
	v_mfma_f32_32x32x16_bf16 v[236:251], v[130:133], v[74:77], v[236:251]
	v_fma_f32 v75, v191, s15, v50
	v_fma_f32 v74, v190, s14, v50
	v_fma_f32 v77, v191, s17, v50
	v_fma_f32 v76, v190, s16, v50
	v_exp_f32_e32 v112, v112
	s_waitcnt lgkmcnt(0)
	v_mfma_f32_32x32x16_bf16 v[200:215], v[130:133], v[78:81], v[200:215]
	v_fma_f32 v79, v191, s19, v50
	v_fma_f32 v78, v190, s18, v50
	v_fma_f32 v81, v191, s21, v50
	v_fma_f32 v80, v190, s20, v50
	v_exp_f32_e32 v113, v113
	v_fma_f32 v53, v185, s37, v50
	v_fma_f32 v52, v184, s36, v50
	v_fma_f32 v51, v189, s93, v50
	v_fma_f32 v50, v188, s92, v50
	s_nop 0
	s_waitcnt vmcnt(3) lgkmcnt(0)
	s_barrier
	s_and_saveexec_b64 s[64:65], s[44:45]
	s_cbranch_execz .LBB0_344
	s_waitcnt lgkmcnt(0)
	ds_read_b128 v[84:87], v227 offset:49248
	ds_read_b128 v[88:91], v227 offset:49216
	ds_read_b128 v[92:95], v227 offset:49184
	s_waitcnt lgkmcnt(2)
	v_pk_mul_f32 v[32:33], v[32:33], v[86:87]
	v_pk_mul_f32 v[30:31], v[30:31], v[84:85]
	v_pk_mul_f32 v[48:49], v[48:49], v[86:87]
	v_pk_mul_f32 v[46:47], v[46:47], v[84:85]
	v_pk_mul_f32 v[250:251], v[250:251], v[86:87]
	v_pk_mul_f32 v[248:249], v[248:249], v[84:85]
	v_pk_mul_f32 v[214:215], v[214:215], v[86:87]
	v_pk_mul_f32 v[212:213], v[212:213], v[84:85]
	ds_read_b128 v[84:87], v227 offset:49152
	s_waitcnt lgkmcnt(2)
	v_pk_mul_f32 v[28:29], v[28:29], v[90:91]
	v_pk_mul_f32 v[26:27], v[26:27], v[88:89]
	v_pk_mul_f32 v[44:45], v[44:45], v[90:91]
	v_pk_mul_f32 v[42:43], v[42:43], v[88:89]
	v_pk_mul_f32 v[246:247], v[246:247], v[90:91]
	v_pk_mul_f32 v[244:245], v[244:245], v[88:89]
	v_pk_mul_f32 v[210:211], v[210:211], v[90:91]
	v_pk_mul_f32 v[208:209], v[208:209], v[88:89]
	s_waitcnt lgkmcnt(1)
	v_pk_mul_f32 v[24:25], v[24:25], v[94:95]
	v_pk_mul_f32 v[22:23], v[22:23], v[92:93]
	v_pk_mul_f32 v[40:41], v[40:41], v[94:95]
	v_pk_mul_f32 v[38:39], v[38:39], v[92:93]
	v_pk_mul_f32 v[242:243], v[242:243], v[94:95]
	v_pk_mul_f32 v[240:241], v[240:241], v[92:93]
	v_pk_mul_f32 v[206:207], v[206:207], v[94:95]
	v_pk_mul_f32 v[204:205], v[204:205], v[92:93]
	s_waitcnt lgkmcnt(0)
	v_pk_mul_f32 v[20:21], v[20:21], v[86:87]
	v_pk_mul_f32 v[18:19], v[18:19], v[84:85]
	v_pk_mul_f32 v[36:37], v[36:37], v[86:87]
	v_pk_mul_f32 v[34:35], v[34:35], v[84:85]
	v_pk_mul_f32 v[238:239], v[238:239], v[86:87]
	v_pk_mul_f32 v[236:237], v[236:237], v[84:85]
	v_pk_mul_f32 v[202:203], v[202:203], v[86:87]
	v_pk_mul_f32 v[200:201], v[200:201], v[84:85]

;   #define RESC() do{ if(resc){ asm volatile("s_waitcnt lgkmcnt(0)":::"memory"); \
;       _Pragma("unroll") for(int d_=0;d_<2;++d_) _Pragma("unroll") for(int r=0;r<16;++r)o[d_][r]*=wsf[crow(r,hi)]; } }while(0)
;   #define ROT() do{sl_prev=sl_cur;sl_cur=sl_next;sl_next=(sl_next==(NSLOT-1)*SLOTB)?0:sl_next+SLOTB;}while(0)
;   #define ENDW(tt) do{ if((tt)+3<NT){WAIT_BAR(2);} else if((tt)+2<NT){WAIT_BAR(1);} else {WAIT_BAR(0);} }while(0)
; template<int THRL> __device__ __forceinline__ void attn_unit(long rowbase,int qb,int t0,bool WIN,bool NOMAX,const bf16*Qc,const bf16*__restrict__ Kc,const bf16*__restrict__ Vc,bf16*Oc,float s2,float sink2,char*shm,
;     bf16x8 (&qr)[4],bool pref,const bf16*qkvb,int vn,int in_){
;     ...
;     STEP(pB0,pB1,pA0,pA1,t,(t+3<NT),(t+1<NT),(t+1<NT));       ENDW(t);   RESC(); ROT();
;     STEP(pA0,pA1,pB0,pB1,t+1,(t+4<NT),(t+2<NT),(t+2<NT));     ENDW(t+1); RESC(); ROT();
.LBB0_522:
	s_andn2_b64 vcc, exec, s[66:67]
	s_cbranch_vccnz .LBB0_524
	s_waitcnt vmcnt(2) lgkmcnt(0)
	s_barrier

;   #define RESC() do{ if(resc){ asm volatile("s_waitcnt lgkmcnt(0)":::"memory"); \
;       _Pragma("unroll") for(int d_=0;d_<2;++d_) _Pragma("unroll") for(int r=0;r<16;++r)o[d_][r]*=wsf[crow(r,hi)]; } }while(0)
;   #define ROT() do{sl_prev=sl_cur;sl_cur=sl_next;sl_next=(sl_next==(NSLOT-1)*SLOTB)?0:sl_next+SLOTB;}while(0)
;   #define ENDW(tt) do{ if((tt)+3<NT){WAIT_BAR(2);} else if((tt)+2<NT){WAIT_BAR(1);} else {WAIT_BAR(0);} }while(0)
; template<int THRL> __device__ __forceinline__ void attn_unit(long rowbase,int qb,int t0,bool WIN,bool NOMAX,const bf16*Qc,const bf16*__restrict__ Kc,const bf16*__restrict__ Vc,bf16*Oc,float s2,float sink2,char*shm,
;     bf16x8 (&qr)[4],bool pref,const bf16*qkvb,int vn,int in_){
;     ...
;     STEP(pB0,pB1,pA0,pA1,t,(t+3<NT),(t+1<NT),(t+1<NT));       ENDW(t);   RESC(); ROT();
;     STEP(pA0,pA1,pB0,pB1,t+1,(t+4<NT),(t+2<NT),(t+2<NT));     ENDW(t+1); RESC(); ROT();
.LBB0_525:
	s_waitcnt vmcnt(3) lgkmcnt(0)
	s_barrier
	s_and_saveexec_b64 s[66:67], s[44:45]
	s_cbranch_execnz .LBB0_433
	s_branch .LBB0_434

;   #define RESC() do{ if(resc){ asm volatile("s_waitcnt lgkmcnt(0)":::"memory"); \
;       _Pragma("unroll") for(int d_=0;d_<2;++d_) _Pragma("unroll") for(int r=0;r<16;++r)o[d_][r]*=wsf[crow(r,hi)]; } }while(0)
;   #define ROT() do{sl_prev=sl_cur;sl_cur=sl_next;sl_next=(sl_next==(NSLOT-1)*SLOTB)?0:sl_next+SLOTB;}while(0)
;   #define ENDW(tt) do{ if((tt)+3<NT){WAIT_BAR(2);} else if((tt)+2<NT){WAIT_BAR(1);} else {WAIT_BAR(0);} }while(0)
; template<int THRL> __device__ __forceinline__ void attn_unit(long rowbase,int qb,int t0,bool WIN,bool NOMAX,const bf16*Qc,const bf16*__restrict__ Kc,const bf16*__restrict__ Vc,bf16*Oc,float s2,float sink2,char*shm,
;     bf16x8 (&qr)[4],bool pref,const bf16*qkvb,int vn,int in_){
;     ...
;     STEP(pB0,pB1,pA0,pA1,t,(t+3<NT),(t+1<NT),(t+1<NT));       ENDW(t);   RESC(); ROT();
;     STEP(pA0,pA1,pB0,pB1,t+1,(t+4<NT),(t+2<NT),(t+2<NT));     ENDW(t+1); RESC(); ROT();
.LBB0_528:
	s_andn2_b64 vcc, exec, s[44:45]
	s_cbranch_vccnz .LBB0_530
	s_waitcnt vmcnt(2) lgkmcnt(0)
	s_barrier

;   #define RESC() do{ if(resc){ asm volatile("s_waitcnt lgkmcnt(0)":::"memory"); \
;       _Pragma("unroll") for(int d_=0;d_<2;++d_) _Pragma("unroll") for(int r=0;r<16;++r)o[d_][r]*=wsf[crow(r,hi)]; } }while(0)
;   #define ROT() do{sl_prev=sl_cur;sl_cur=sl_next;sl_next=(sl_next==(NSLOT-1)*SLOTB)?0:sl_next+SLOTB;}while(0)
;   #define ENDW(tt) do{ if((tt)+3<NT){WAIT_BAR(2);} else if((tt)+2<NT){WAIT_BAR(1);} else {WAIT_BAR(0);} }while(0)
; template<int THRL> __device__ __forceinline__ void attn_unit(long rowbase,int qb,int t0,bool WIN,bool NOMAX,const bf16*Qc,const bf16*__restrict__ Kc,const bf16*__restrict__ Vc,bf16*Oc,float s2,float sink2,char*shm,
;     bf16x8 (&qr)[4],bool pref,const bf16*qkvb,int vn,int in_){
;     ...
;     STEP(pB0,pB1,pA0,pA1,t,(t+3<NT),(t+1<NT),(t+1<NT));       ENDW(t);   RESC(); ROT();
;     STEP(pA0,pA1,pB0,pB1,t+1,(t+4<NT),(t+2<NT),(t+2<NT));     ENDW(t+1); RESC(); ROT();
.LBB0_531:
	s_waitcnt vmcnt(3) lgkmcnt(0)
	s_barrier
	s_and_saveexec_b64 s[44:45], s[70:71]
	s_cbranch_execnz .LBB0_517
	s_branch .LBB0_518
